# up-GEMM: leading half starts its SwiGLU epilogue (2 row groups) before the alignment barrier, overlapping the trailing half's last MFMA block
# baseline (speedup 1.0000x reference)
; #define PG8_BAR __builtin_amdgcn_s_barrier()
; __device__ __forceinline__ u32x4 pack8(const f32x4 a, const f32x4 b) { u32x4 w; w.x = cvt_pk_bf16(a[0], a[1]); w.y = cvt_pk_bf16(a[2], a[3]); w.z = cvt_pk_bf16(b[0], b[1]); w.w = cvt_pk_bf16(b[2], b[3]); return w; }
; template <class Epi, class Sched, bool ALIGN_EPI = false, bool SP2 = false>
; __device__ __forceinline__ void gemm_phase(PG8_LAS unsigned char* lds, const Gemm g, const Sched& S, const Epi& E) {
;     ...
;         if constexpr (ALIGN_EPI) { if (wr == 0) PG8_BAR; }
;     __device__ __forceinline__ void operator()(const f32x4 (&acc)[2][2][4][2], const Unit& u, int wr, int wc, int fr, int fq) const {
;         const int row0 = u.pm * 256 + wr * 64 + fr, col0 = u.pn * 128 + wc * 32 + 8 * fq;
;         float rsv[2][4]; { int frl = fr; asm volatile("" : "+v"(frl));
;             const LAS float* t = RSL + ((u.pm >> 3) & 3) * 256 + wr * 64 + frl;
; #pragma unroll
;             for (int ai = 0; ai < 2; ++ai)
; #pragma unroll
;                 for (int m = 0; m < 4; ++m) rsv[ai][m] = t[ai * 128 + m * 16]; }
; #pragma unroll
;         for (int ai = 0; ai < 2; ++ai)
; #pragma unroll
;             for (int m = 0; m < 4; ++m) { f32x4 v[2]; const float rs = rsv[ai][m], rsl = rs * -1.4426950408889634f, rs2 = rs * rs;
; #pragma unroll
;                 for (int n = 0; n < 2; ++n) {
;                     const f32x4 gt = acc[ai][0][m][n], up = acc[ai][1][m][n]; const f32x4 pr = gt * up, ar = gt * rsl; f32x4 ex;
; #pragma unroll
;                     for (int e = 0; e < 4; ++e) ex[e] = __builtin_amdgcn_exp2f(ar[e]);
;                     const f32x4 dn = ex + 1.0f; f32x4 rc;
; #pragma unroll
;                     for (int e = 0; e < 4; ++e) rc[e] = __builtin_amdgcn_rcpf(dn[e]);
;                     v[n] = (pr * rs2) * rc; }
;                 __builtin_nontemporal_store(pack8(v[0], v[1]), (u32x4*)(O + (size_t)(row0 + ai * 128 + m * 16) * DFF + col0)); }
.Lpk_done_up:
.LBB0_1215:
	s_lshl_b32 s8, s61, 7
	v_mov_b32_e32 v140, v144
	s_and_b32 s8, s8, 0xc00
	s_add_i32 s8, s58, s8
	v_lshl_add_u32 v140, v140, 2, s8
	ds_read2_b32 v[150:151], v140 offset1:16
	ds_read2_b32 v[152:153], v140 offset0:32 offset1:48
	ds_read2_b32 v[142:143], v140 offset0:128 offset1:144
	ds_read2_b32 v[140:141], v140 offset0:160 offset1:176
	v_pk_mul_f32 v[124:125], v[128:129], v[124:125]
	s_waitcnt lgkmcnt(0)
	v_mul_f32_e32 v156, 0xbfb8aa3b, v150
	v_pk_mul_f32 v[160:161], v[126:127], v[156:157] op_sel_hi:[1,0]
	v_pk_mul_f32 v[158:159], v[128:129], v[156:157] op_sel_hi:[1,0]
	v_exp_f32_e32 v157, v160
	v_exp_f32_e32 v160, v161
	v_exp_f32_e32 v161, v158
	v_exp_f32_e32 v162, v159
	v_add_f32_e32 v157, 1.0, v157
	v_rcp_f32_e32 v158, v157
	v_add_f32_e32 v157, 1.0, v160
	v_rcp_f32_e32 v159, v157
	v_add_f32_e32 v157, 1.0, v161
	v_rcp_f32_e32 v160, v157
	v_add_f32_e32 v157, 1.0, v162
	v_pk_mul_f32 v[128:129], v[118:119], v[156:157] op_sel_hi:[1,0]
	v_pk_mul_f32 v[122:123], v[126:127], v[122:123]
	v_pk_mul_f32 v[126:127], v[120:121], v[156:157] op_sel_hi:[1,0]
	v_exp_f32_e32 v128, v128
	v_exp_f32_e32 v129, v129
	v_rcp_f32_e32 v161, v157
	v_exp_f32_e32 v156, v126
	v_exp_f32_e32 v157, v127
	v_add_f32_e32 v126, 1.0, v128
	v_add_f32_e32 v127, 1.0, v129
	v_rcp_f32_e32 v126, v126
	v_rcp_f32_e32 v127, v127
	v_add_f32_e32 v128, 1.0, v156
	v_add_f32_e32 v129, 1.0, v157
	v_rcp_f32_e32 v128, v128
	v_rcp_f32_e32 v129, v129
	v_mul_f32_e32 v150, v150, v150
	v_pk_mul_f32 v[114:115], v[118:119], v[114:115]
	v_pk_mul_f32 v[116:117], v[120:121], v[116:117]
	v_pk_mul_f32 v[114:115], v[114:115], v[150:151] op_sel_hi:[1,0]
	v_lshl_or_b32 v154, s60, 7, v147
	v_pk_mul_f32 v[122:123], v[122:123], v[150:151] op_sel_hi:[1,0]
	v_pk_mul_f32 v[124:125], v[124:125], v[150:151] op_sel_hi:[1,0]
	v_pk_mul_f32 v[116:117], v[116:117], v[150:151] op_sel_hi:[1,0]
	v_pk_mul_f32 v[114:115], v[114:115], v[126:127]
	v_lshl_add_u32 v149, s61, 8, v145
	v_ashrrev_i32_e32 v155, 31, v154
	v_pk_mul_f32 v[124:125], v[124:125], v[160:161]
	v_pk_mul_f32 v[122:123], v[122:123], v[158:159]
	v_pk_mul_f32 v[116:117], v[116:117], v[128:129]
	v_cvt_pk_bf16_f32 v118, v122, v123
	v_cvt_pk_bf16_f32 v119, v124, v125
	v_cvt_pk_bf16_f32 v120, v114, v115
	v_mov_b64_e32 v[114:115], s[14:15]
	v_cvt_pk_bf16_f32 v121, v116, v117
	v_mad_i64_i32 v[122:123], s[8:9], v149, s65, v[114:115]
	v_lshlrev_b64 v[116:117], 1, v[154:155]
	v_lshl_add_u64 v[122:123], v[122:123], 0, v[116:117]
	global_store_dwordx4 v[122:123], v[118:121], off nt
	v_pk_mul_f32 v[108:109], v[112:113], v[108:109]
	v_pk_mul_f32 v[106:107], v[110:111], v[106:107]
	v_mul_f32_e32 v118, 0xbfb8aa3b, v151
	v_pk_mul_f32 v[124:125], v[110:111], v[118:119] op_sel_hi:[1,0]
	v_pk_mul_f32 v[122:123], v[112:113], v[118:119] op_sel_hi:[1,0]
	v_exp_f32_e32 v119, v124
	v_exp_f32_e32 v121, v125
	v_exp_f32_e32 v124, v122
	v_exp_f32_e32 v125, v123
	v_add_f32_e32 v119, 1.0, v119
	v_rcp_f32_e32 v122, v119
	v_add_f32_e32 v119, 1.0, v121
	v_rcp_f32_e32 v123, v119
	v_add_f32_e32 v119, 1.0, v124
	v_rcp_f32_e32 v124, v119
	v_add_f32_e32 v119, 1.0, v125
	v_pk_mul_f32 v[110:111], v[104:105], v[118:119] op_sel_hi:[1,0]
	v_pk_mul_f32 v[112:113], v[102:103], v[118:119] op_sel_hi:[1,0]
	v_rcp_f32_e32 v125, v119
	v_exp_f32_e32 v112, v112
	v_exp_f32_e32 v113, v113
	v_exp_f32_e32 v118, v110
	v_exp_f32_e32 v119, v111
	v_add_f32_e32 v110, 1.0, v112
	v_add_f32_e32 v111, 1.0, v113
	v_add_f32_e32 v112, 1.0, v118
	v_add_f32_e32 v113, 1.0, v119
	v_rcp_f32_e32 v110, v110
	v_rcp_f32_e32 v111, v111
	v_rcp_f32_e32 v112, v112
	v_rcp_f32_e32 v113, v113
	v_mul_f32_e32 v120, v151, v151
	v_pk_mul_f32 v[100:101], v[104:105], v[100:101]
	v_pk_mul_f32 v[98:99], v[102:103], v[98:99]
	v_pk_mul_f32 v[100:101], v[100:101], v[120:121] op_sel_hi:[1,0]
	v_pk_mul_f32 v[98:99], v[98:99], v[120:121] op_sel_hi:[1,0]
	v_pk_mul_f32 v[106:107], v[106:107], v[120:121] op_sel_hi:[1,0]
	v_pk_mul_f32 v[108:109], v[108:109], v[120:121] op_sel_hi:[1,0]
	v_pk_mul_f32 v[102:103], v[100:101], v[112:113]
	v_pk_mul_f32 v[100:101], v[98:99], v[110:111]
	v_pk_mul_f32 v[108:109], v[108:109], v[124:125]
	v_pk_mul_f32 v[106:107], v[106:107], v[122:123]
	v_pk_mul_f32 v[92:93], v[96:97], v[92:93]
	v_cvt_pk_bf16_f32 v98, v106, v107
	v_cvt_pk_bf16_f32 v99, v108, v109
	v_cvt_pk_bf16_f32 v100, v100, v101
	v_cvt_pk_bf16_f32 v101, v102, v103
	v_or_b32_e32 v102, 16, v149
	v_mad_i64_i32 v[102:103], s[8:9], v102, s65, v[114:115]
	v_lshl_add_u64 v[102:103], v[102:103], 0, v[116:117]
	global_store_dwordx4 v[102:103], v[98:101], off nt
	s_and_b64 vcc, exec, s[16:17]
	s_cbranch_vccz .Lepi_up_nb
	s_barrier
; __device__ __forceinline__ u32x4 pack8(const f32x4 a, const f32x4 b) { u32x4 w; w.x = cvt_pk_bf16(a[0], a[1]); w.y = cvt_pk_bf16(a[2], a[3]); w.z = cvt_pk_bf16(b[0], b[1]); w.w = cvt_pk_bf16(b[2], b[3]); return w; }
;     __device__ __forceinline__ void operator()(const f32x4 (&acc)[2][2][4][2], const Unit& u, int wr, int wc, int fr, int fq) const {
;     ...
; #pragma unroll
;         for (int ai = 0; ai < 2; ++ai)
; #pragma unroll
;             for (int m = 0; m < 4; ++m) { f32x4 v[2]; const float rs = rsv[ai][m], rsl = rs * -1.4426950408889634f, rs2 = rs * rs;
; #pragma unroll
;                 for (int n = 0; n < 2; ++n) {
;                     const f32x4 gt = acc[ai][0][m][n], up = acc[ai][1][m][n]; const f32x4 pr = gt * up, ar = gt * rsl; f32x4 ex;
; #pragma unroll
;                     for (int e = 0; e < 4; ++e) ex[e] = __builtin_amdgcn_exp2f(ar[e]);
;                     const f32x4 dn = ex + 1.0f; f32x4 rc;
; #pragma unroll
;                     for (int e = 0; e < 4; ++e) rc[e] = __builtin_amdgcn_rcpf(dn[e]);
;                     v[n] = (pr * rs2) * rc; }
;                 __builtin_nontemporal_store(pack8(v[0], v[1]), (u32x4*)(O + (size_t)(row0 + ai * 128 + m * 16) * DFF + col0)); }
.Lepi_up_nb:
	v_pk_mul_f32 v[90:91], v[94:95], v[90:91]
	v_pk_mul_f32 v[84:85], v[88:89], v[84:85]
	v_mul_f32_e32 v98, 0xbfb8aa3b, v152
	v_pk_mul_f32 v[104:105], v[94:95], v[98:99] op_sel_hi:[1,0]
	v_pk_mul_f32 v[102:103], v[96:97], v[98:99] op_sel_hi:[1,0]
	v_exp_f32_e32 v99, v104
	v_exp_f32_e32 v101, v105
	v_exp_f32_e32 v104, v102
	v_exp_f32_e32 v105, v103
	v_add_f32_e32 v99, 1.0, v99
	v_rcp_f32_e32 v102, v99
	v_add_f32_e32 v99, 1.0, v101
	v_rcp_f32_e32 v103, v99
	v_add_f32_e32 v99, 1.0, v104
	v_rcp_f32_e32 v104, v99
	v_add_f32_e32 v99, 1.0, v105
	v_pk_mul_f32 v[94:95], v[88:89], v[98:99] op_sel_hi:[1,0]
	v_pk_mul_f32 v[96:97], v[86:87], v[98:99] op_sel_hi:[1,0]
	v_rcp_f32_e32 v105, v99
	v_exp_f32_e32 v96, v96
	v_exp_f32_e32 v97, v97
	v_exp_f32_e32 v98, v94
	v_exp_f32_e32 v99, v95
	v_add_f32_e32 v94, 1.0, v96
	v_add_f32_e32 v95, 1.0, v97
	v_add_f32_e32 v96, 1.0, v98
	v_add_f32_e32 v97, 1.0, v99
	v_rcp_f32_e32 v94, v94
	v_rcp_f32_e32 v95, v95
	v_rcp_f32_e32 v96, v96
	v_rcp_f32_e32 v97, v97
	v_mul_f32_e32 v100, v152, v152
	v_pk_mul_f32 v[82:83], v[86:87], v[82:83]
	v_pk_mul_f32 v[84:85], v[84:85], v[100:101] op_sel_hi:[1,0]
	v_pk_mul_f32 v[82:83], v[82:83], v[100:101] op_sel_hi:[1,0]
	v_pk_mul_f32 v[90:91], v[90:91], v[100:101] op_sel_hi:[1,0]
	v_pk_mul_f32 v[92:93], v[92:93], v[100:101] op_sel_hi:[1,0]
	v_pk_mul_f32 v[86:87], v[84:85], v[96:97]
	v_pk_mul_f32 v[84:85], v[82:83], v[94:95]
	v_pk_mul_f32 v[92:93], v[92:93], v[104:105]
	v_pk_mul_f32 v[90:91], v[90:91], v[102:103]
	v_pk_mul_f32 v[76:77], v[80:81], v[76:77]
	v_cvt_pk_bf16_f32 v82, v90, v91
	v_cvt_pk_bf16_f32 v83, v92, v93
	v_cvt_pk_bf16_f32 v84, v84, v85
	v_cvt_pk_bf16_f32 v85, v86, v87
	v_or_b32_e32 v86, 32, v149
	v_mad_i64_i32 v[86:87], s[8:9], v86, s65, v[114:115]
	v_lshl_add_u64 v[86:87], v[86:87], 0, v[116:117]
	global_store_dwordx4 v[86:87], v[82:85], off nt
	v_pk_mul_f32 v[74:75], v[78:79], v[74:75]
	v_pk_mul_f32 v[68:69], v[72:73], v[68:69]
	v_mul_f32_e32 v82, 0xbfb8aa3b, v153
	v_pk_mul_f32 v[88:89], v[78:79], v[82:83] op_sel_hi:[1,0]
	v_pk_mul_f32 v[86:87], v[80:81], v[82:83] op_sel_hi:[1,0]
	v_exp_f32_e32 v83, v88
	v_exp_f32_e32 v85, v89
	v_exp_f32_e32 v88, v86
	v_exp_f32_e32 v89, v87
	v_add_f32_e32 v83, 1.0, v83
	v_rcp_f32_e32 v86, v83
	v_add_f32_e32 v83, 1.0, v85
	v_rcp_f32_e32 v87, v83
	v_add_f32_e32 v83, 1.0, v88
	v_rcp_f32_e32 v88, v83
	v_add_f32_e32 v83, 1.0, v89
	v_pk_mul_f32 v[78:79], v[72:73], v[82:83] op_sel_hi:[1,0]
	v_pk_mul_f32 v[80:81], v[70:71], v[82:83] op_sel_hi:[1,0]
	v_rcp_f32_e32 v89, v83
	v_exp_f32_e32 v80, v80
	v_exp_f32_e32 v81, v81
	v_exp_f32_e32 v82, v78
	v_exp_f32_e32 v83, v79
	v_add_f32_e32 v78, 1.0, v80
	v_add_f32_e32 v79, 1.0, v81
	v_add_f32_e32 v80, 1.0, v82
	v_add_f32_e32 v81, 1.0, v83
	v_rcp_f32_e32 v78, v78
	v_rcp_f32_e32 v79, v79
	v_rcp_f32_e32 v80, v80
	v_rcp_f32_e32 v81, v81
	v_mul_f32_e32 v84, v153, v153
	v_pk_mul_f32 v[66:67], v[70:71], v[66:67]
	v_pk_mul_f32 v[68:69], v[68:69], v[84:85] op_sel_hi:[1,0]
	v_pk_mul_f32 v[66:67], v[66:67], v[84:85] op_sel_hi:[1,0]
	v_pk_mul_f32 v[74:75], v[74:75], v[84:85] op_sel_hi:[1,0]
	v_pk_mul_f32 v[76:77], v[76:77], v[84:85] op_sel_hi:[1,0]
	v_pk_mul_f32 v[70:71], v[68:69], v[80:81]
	v_pk_mul_f32 v[68:69], v[66:67], v[78:79]
	v_pk_mul_f32 v[76:77], v[76:77], v[88:89]
	v_pk_mul_f32 v[74:75], v[74:75], v[86:87]
	v_pk_mul_f32 v[60:61], v[64:65], v[60:61]
	v_cvt_pk_bf16_f32 v66, v74, v75
	v_cvt_pk_bf16_f32 v67, v76, v77
	v_cvt_pk_bf16_f32 v68, v68, v69
	v_cvt_pk_bf16_f32 v69, v70, v71
	v_or_b32_e32 v70, 48, v149
	v_mad_i64_i32 v[70:71], s[8:9], v70, s65, v[114:115]
	v_lshl_add_u64 v[70:71], v[70:71], 0, v[116:117]
	global_store_dwordx4 v[70:71], v[66:69], off nt
	v_pk_mul_f32 v[58:59], v[62:63], v[58:59]
	v_pk_mul_f32 v[52:53], v[56:57], v[52:53]
	v_add_u32_e32 v67, 0x80, v149
	v_mul_f32_e32 v66, 0xbfb8aa3b, v142
	v_pk_mul_f32 v[72:73], v[62:63], v[66:67] op_sel_hi:[1,0]
	v_pk_mul_f32 v[70:71], v[64:65], v[66:67] op_sel_hi:[1,0]
	v_exp_f32_e32 v69, v72
	v_exp_f32_e32 v72, v73
	v_exp_f32_e32 v73, v70
	v_exp_f32_e32 v74, v71
	v_add_f32_e32 v69, 1.0, v69
	v_rcp_f32_e32 v70, v69
	v_add_f32_e32 v69, 1.0, v72
	v_rcp_f32_e32 v71, v69
	v_add_f32_e32 v69, 1.0, v73
	v_mul_f32_e32 v68, v142, v142
	v_rcp_f32_e32 v72, v69
	v_add_f32_e32 v69, 1.0, v74
	v_pk_mul_f32 v[62:63], v[56:57], v[66:67] op_sel_hi:[1,0]
	v_pk_mul_f32 v[64:65], v[54:55], v[66:67] op_sel_hi:[1,0]
	v_rcp_f32_e32 v73, v69
	v_pk_mul_f32 v[58:59], v[58:59], v[68:69] op_sel_hi:[1,0]
	v_pk_mul_f32 v[60:61], v[60:61], v[68:69] op_sel_hi:[1,0]
	v_exp_f32_e32 v64, v64
	v_exp_f32_e32 v65, v65
	v_exp_f32_e32 v66, v62
	v_exp_f32_e32 v69, v63
	v_add_f32_e32 v62, 1.0, v64
	v_add_f32_e32 v63, 1.0, v65
	v_add_f32_e32 v64, 1.0, v66
	v_add_f32_e32 v65, 1.0, v69
	v_rcp_f32_e32 v62, v62
	v_rcp_f32_e32 v63, v63
	v_rcp_f32_e32 v64, v64
	v_rcp_f32_e32 v65, v65
	v_pk_mul_f32 v[50:51], v[54:55], v[50:51]
	v_pk_mul_f32 v[52:53], v[52:53], v[68:69] op_sel_hi:[1,0]
	v_pk_mul_f32 v[50:51], v[50:51], v[68:69] op_sel_hi:[1,0]
	v_pk_mul_f32 v[54:55], v[52:53], v[64:65]
	v_pk_mul_f32 v[52:53], v[50:51], v[62:63]
	v_pk_mul_f32 v[60:61], v[60:61], v[72:73]
	v_pk_mul_f32 v[58:59], v[58:59], v[70:71]
	v_pk_mul_f32 v[44:45], v[48:49], v[44:45]
	v_cvt_pk_bf16_f32 v50, v58, v59
	v_cvt_pk_bf16_f32 v51, v60, v61
	v_cvt_pk_bf16_f32 v52, v52, v53
	v_cvt_pk_bf16_f32 v53, v54, v55
	v_mad_i64_i32 v[54:55], s[8:9], v67, s65, v[114:115]
	v_lshl_add_u64 v[54:55], v[54:55], 0, v[116:117]
	global_store_dwordx4 v[54:55], v[50:53], off nt
; #define PG8_BAR __builtin_amdgcn_s_barrier()
; __device__ __forceinline__ u32x4 pack8(const f32x4 a, const f32x4 b) { u32x4 w; w.x = cvt_pk_bf16(a[0], a[1]); w.y = cvt_pk_bf16(a[2], a[3]); w.z = cvt_pk_bf16(b[0], b[1]); w.w = cvt_pk_bf16(b[2], b[3]); return w; }
; template <class Epi, class Sched, bool ALIGN_EPI = false, bool SP2 = false>
; __device__ __forceinline__ void gemm_phase(PG8_LAS unsigned char* lds, const Gemm g, const Sched& S, const Epi& E) {
;     ...
;         if (!has_next) break;
; #pragma unroll
;         for (int a = 0; a < 2; ++a)
; #pragma unroll
;             for (int b = 0; b < 2; ++b)
; #pragma unroll
;                 for (int m = 0; m < 4; ++m)
; #pragma unroll
;                     for (int n = 0; n < 2; ++n) acc[a][b][m][n] = (f32x4){0.f, 0.f, 0.f, 0.f};
;         cur = nxt; cA = nA; cB = nB; ++ui;
;         if constexpr (ALIGN_EPI) { if (wr == 1) PG8_BAR; }
;     __device__ __forceinline__ void operator()(const f32x4 (&acc)[2][2][4][2], const Unit& u, int wr, int wc, int fr, int fq) const {
;     ...
; #pragma unroll
;         for (int ai = 0; ai < 2; ++ai)
; #pragma unroll
;             for (int m = 0; m < 4; ++m) { f32x4 v[2]; const float rs = rsv[ai][m], rsl = rs * -1.4426950408889634f, rs2 = rs * rs;
; #pragma unroll
;                 for (int n = 0; n < 2; ++n) {
;                     const f32x4 gt = acc[ai][0][m][n], up = acc[ai][1][m][n]; const f32x4 pr = gt * up, ar = gt * rsl; f32x4 ex;
; #pragma unroll
;                     for (int e = 0; e < 4; ++e) ex[e] = __builtin_amdgcn_exp2f(ar[e]);
;                     const f32x4 dn = ex + 1.0f; f32x4 rc;
; #pragma unroll
;                     for (int e = 0; e < 4; ++e) rc[e] = __builtin_amdgcn_rcpf(dn[e]);
;                     v[n] = (pr * rs2) * rc; }
;                 __builtin_nontemporal_store(pack8(v[0], v[1]), (u32x4*)(O + (size_t)(row0 + ai * 128 + m * 16) * DFF + col0)); }
	v_pk_mul_f32 v[42:43], v[46:47], v[42:43]
	v_pk_mul_f32 v[36:37], v[40:41], v[36:37]
	v_mul_f32_e32 v50, 0xbfb8aa3b, v143
	v_pk_mul_f32 v[56:57], v[46:47], v[50:51] op_sel_hi:[1,0]
	v_pk_mul_f32 v[54:55], v[48:49], v[50:51] op_sel_hi:[1,0]
	v_exp_f32_e32 v51, v56
	v_exp_f32_e32 v53, v57
	v_exp_f32_e32 v56, v54
	v_exp_f32_e32 v57, v55
	v_add_f32_e32 v51, 1.0, v51
	v_rcp_f32_e32 v54, v51
	v_add_f32_e32 v51, 1.0, v53
	v_rcp_f32_e32 v55, v51
	v_add_f32_e32 v51, 1.0, v56
	v_rcp_f32_e32 v56, v51
	v_add_f32_e32 v51, 1.0, v57
	v_pk_mul_f32 v[46:47], v[40:41], v[50:51] op_sel_hi:[1,0]
	v_pk_mul_f32 v[48:49], v[38:39], v[50:51] op_sel_hi:[1,0]
	v_rcp_f32_e32 v57, v51
	v_exp_f32_e32 v48, v48
	v_exp_f32_e32 v49, v49
	v_exp_f32_e32 v50, v46
	v_exp_f32_e32 v51, v47
	v_add_f32_e32 v46, 1.0, v48
	v_add_f32_e32 v47, 1.0, v49
	v_add_f32_e32 v48, 1.0, v50
	v_add_f32_e32 v49, 1.0, v51
	v_rcp_f32_e32 v46, v46
	v_rcp_f32_e32 v47, v47
	v_rcp_f32_e32 v48, v48
	v_rcp_f32_e32 v49, v49
	v_mul_f32_e32 v52, v143, v143
	v_pk_mul_f32 v[34:35], v[38:39], v[34:35]
	v_pk_mul_f32 v[36:37], v[36:37], v[52:53] op_sel_hi:[1,0]
	v_pk_mul_f32 v[34:35], v[34:35], v[52:53] op_sel_hi:[1,0]
	v_pk_mul_f32 v[42:43], v[42:43], v[52:53] op_sel_hi:[1,0]
	v_pk_mul_f32 v[44:45], v[44:45], v[52:53] op_sel_hi:[1,0]
	v_pk_mul_f32 v[38:39], v[36:37], v[48:49]
	v_pk_mul_f32 v[36:37], v[34:35], v[46:47]
	v_pk_mul_f32 v[44:45], v[44:45], v[56:57]
	v_pk_mul_f32 v[42:43], v[42:43], v[54:55]
	v_pk_mul_f32 v[28:29], v[32:33], v[28:29]
	v_cvt_pk_bf16_f32 v34, v42, v43
	v_cvt_pk_bf16_f32 v35, v44, v45
	v_cvt_pk_bf16_f32 v36, v36, v37
	v_cvt_pk_bf16_f32 v37, v38, v39
	v_add_u32_e32 v38, 0x90, v149
	v_mad_i64_i32 v[38:39], s[8:9], v38, s65, v[114:115]
	v_lshl_add_u64 v[38:39], v[38:39], 0, v[116:117]
	global_store_dwordx4 v[38:39], v[34:37], off nt
	v_pk_mul_f32 v[26:27], v[30:31], v[26:27]
	v_pk_mul_f32 v[20:21], v[24:25], v[20:21]
	v_mul_f32_e32 v34, 0xbfb8aa3b, v140
	v_pk_mul_f32 v[40:41], v[30:31], v[34:35] op_sel_hi:[1,0]
	v_pk_mul_f32 v[38:39], v[32:33], v[34:35] op_sel_hi:[1,0]
	v_exp_f32_e32 v35, v40
	v_exp_f32_e32 v37, v41
	v_exp_f32_e32 v40, v38
	v_exp_f32_e32 v41, v39
	v_add_f32_e32 v35, 1.0, v35
	v_rcp_f32_e32 v38, v35
	v_add_f32_e32 v35, 1.0, v37
	v_rcp_f32_e32 v39, v35
	v_add_f32_e32 v35, 1.0, v40
	v_rcp_f32_e32 v40, v35
	v_add_f32_e32 v35, 1.0, v41
	v_pk_mul_f32 v[30:31], v[24:25], v[34:35] op_sel_hi:[1,0]
	v_pk_mul_f32 v[32:33], v[22:23], v[34:35] op_sel_hi:[1,0]
	v_rcp_f32_e32 v41, v35
	v_exp_f32_e32 v32, v32
	v_exp_f32_e32 v33, v33
	v_exp_f32_e32 v34, v30
	v_exp_f32_e32 v35, v31
	v_add_f32_e32 v30, 1.0, v32
	v_add_f32_e32 v31, 1.0, v33
	v_add_f32_e32 v32, 1.0, v34
	v_add_f32_e32 v33, 1.0, v35
	v_rcp_f32_e32 v30, v30
	v_rcp_f32_e32 v31, v31
	v_rcp_f32_e32 v32, v32
	v_rcp_f32_e32 v33, v33
	v_mul_f32_e32 v36, v140, v140
	v_pk_mul_f32 v[18:19], v[22:23], v[18:19]
	v_pk_mul_f32 v[20:21], v[20:21], v[36:37] op_sel_hi:[1,0]
	v_pk_mul_f32 v[18:19], v[18:19], v[36:37] op_sel_hi:[1,0]
	v_pk_mul_f32 v[26:27], v[26:27], v[36:37] op_sel_hi:[1,0]
	v_pk_mul_f32 v[28:29], v[28:29], v[36:37] op_sel_hi:[1,0]
	v_pk_mul_f32 v[22:23], v[20:21], v[32:33]
	v_pk_mul_f32 v[20:21], v[18:19], v[30:31]
	v_pk_mul_f32 v[28:29], v[28:29], v[40:41]
	v_pk_mul_f32 v[26:27], v[26:27], v[38:39]
	v_pk_mul_f32 v[12:13], v[16:17], v[12:13]
	v_cvt_pk_bf16_f32 v18, v26, v27
	v_cvt_pk_bf16_f32 v19, v28, v29
	v_cvt_pk_bf16_f32 v20, v20, v21
	v_cvt_pk_bf16_f32 v21, v22, v23
	v_add_u32_e32 v22, 0xa0, v149
	v_mad_i64_i32 v[22:23], s[8:9], v22, s65, v[114:115]
	v_lshl_add_u64 v[22:23], v[22:23], 0, v[116:117]
	global_store_dwordx4 v[22:23], v[18:21], off nt
	v_pk_mul_f32 v[10:11], v[14:15], v[10:11]
	v_pk_mul_f32 v[4:5], v[8:9], v[4:5]
	v_mul_f32_e32 v18, 0xbfb8aa3b, v141
	v_pk_mul_f32 v[24:25], v[14:15], v[18:19] op_sel_hi:[1,0]
	v_pk_mul_f32 v[22:23], v[16:17], v[18:19] op_sel_hi:[1,0]
	v_exp_f32_e32 v19, v24
	v_exp_f32_e32 v21, v25
	v_exp_f32_e32 v24, v22
	v_exp_f32_e32 v25, v23
	v_add_f32_e32 v19, 1.0, v19
	v_rcp_f32_e32 v22, v19
	v_add_f32_e32 v19, 1.0, v21
	v_rcp_f32_e32 v23, v19
	v_add_f32_e32 v19, 1.0, v24
	v_rcp_f32_e32 v24, v19
	v_add_f32_e32 v19, 1.0, v25
	v_pk_mul_f32 v[14:15], v[8:9], v[18:19] op_sel_hi:[1,0]
	v_pk_mul_f32 v[16:17], v[6:7], v[18:19] op_sel_hi:[1,0]
	v_rcp_f32_e32 v25, v19
	v_exp_f32_e32 v16, v16
	v_exp_f32_e32 v17, v17
	v_exp_f32_e32 v18, v14
	v_exp_f32_e32 v19, v15
	v_add_f32_e32 v14, 1.0, v16
	v_add_f32_e32 v15, 1.0, v17
	v_add_f32_e32 v16, 1.0, v18
	v_add_f32_e32 v17, 1.0, v19
	v_rcp_f32_e32 v14, v14
	v_rcp_f32_e32 v15, v15
	v_rcp_f32_e32 v16, v16
	v_rcp_f32_e32 v17, v17
	v_mul_f32_e32 v20, v141, v141
	v_pk_mul_f32 v[2:3], v[6:7], v[2:3]
	v_pk_mul_f32 v[4:5], v[4:5], v[20:21] op_sel_hi:[1,0]
	v_pk_mul_f32 v[2:3], v[2:3], v[20:21] op_sel_hi:[1,0]
	v_pk_mul_f32 v[10:11], v[10:11], v[20:21] op_sel_hi:[1,0]
	v_pk_mul_f32 v[12:13], v[12:13], v[20:21] op_sel_hi:[1,0]
	v_pk_mul_f32 v[6:7], v[4:5], v[16:17]
	v_pk_mul_f32 v[4:5], v[2:3], v[14:15]
	v_pk_mul_f32 v[12:13], v[12:13], v[24:25]
	v_pk_mul_f32 v[10:11], v[10:11], v[22:23]
	s_andn2_b64 vcc, exec, s[42:43]
	v_cvt_pk_bf16_f32 v2, v10, v11
	v_cvt_pk_bf16_f32 v3, v12, v13
	v_cvt_pk_bf16_f32 v4, v4, v5
	v_cvt_pk_bf16_f32 v5, v6, v7
	v_add_u32_e32 v6, 0xb0, v149
	v_mad_i64_i32 v[6:7], s[8:9], v6, s65, v[114:115]
	v_lshl_add_u64 v[6:7], v[6:7], 0, v[116:117]
	s_mov_b64 s[8:9], -1
	global_store_dwordx4 v[6:7], v[2:5], off nt
	s_cbranch_vccnz .LBB0_1208
	s_andn2_b64 vcc, exec, s[12:13]
	s_cbranch_vccnz .LBB0_1207
	s_barrier
	s_branch .LBB0_1207
